# gate/up GEMM epilogue staged through LDS: full 256-byte row write-back (8 dwordx4 per wave instead of 16 dwordx2 row fragments)
# speedup vs baseline: 1.0118x; 1.0118x over previous
; #define SCHED __builtin_amdgcn_sched_barrier(0)
; template <int EPI>
; DI void gemm_phase(const int wid_s, const h16* __restrict__ A, const h16* __restrict__ Bt, const int N, const int K, const EpiArgs ea) {
;     ...
;     for (int ai = 0; ai < 2; ++ai)
; #pragma unroll
;       for (int m = 0; m < 4; ++m) {
;         const size_t row = (size_t)(brow + ai * HALF + wr * 64 + m * 16 + fr);
; #pragma unroll
;         for (int bj = 0; bj < 2; ++bj) {
;           const int col0 = bcol + bj * HALF + wc * 32 + 8 * fq;
;           const f32x4 v0 = acc[ai][bj][m][0], v1 = acc[ai][bj][m][1];
;           if (EPI == 0) {
;             half8 o = {(h16)v0[0], (h16)v0[1], (h16)v0[2], (h16)v0[3], (h16)v1[0], (h16)v1[1], (h16)v1[2], (h16)v1[3]};
;             *(half8*)(ea.out + row * LDH + col0) = o;
;           } else if (EPI == 1) {
;             const half8 r = *(const half8*)(ea.res + row * 1024 + col0);
;             half8 o;
; #pragma unroll
;             for (int j = 0; j < 4; ++j) { o[j] = (h16)(ALPHA_F * (float)r[j] + v0[j]); o[4 + j] = (h16)(ALPHA_F * (float)r[4 + j] + v1[j]); }
;             *(half8*)(ea.out + row * 1024 + col0) = o;
;           } else {
;             const int f0 = (bcol + bj * HALF + wc * 32) / 2 + 4 * fq;
;             half4 o;
; #pragma unroll
;             for (int j = 0; j < 4; ++j) { const float g = v0[j], u = v1[j]; o[j] = (h16)(g * __builtin_amdgcn_rcpf(1.f + __builtin_amdgcn_exp2f(g * -1.4426950408889634f)) * u); }
;             *(half4*)(ea.out + row * DFF + f0) = o;
;           }
;         }
;         SCHED;
.LBB0_144:
	v_readlane_b32 s11, v252, 24
	v_mbcnt_lo_u32_b32 v186, -1, 0
	v_mbcnt_hi_u32_b32 v186, -1, v186
	v_and_b32_e32 v187, 15, v186
	v_lshrrev_b32_e32 v188, 4, v186
	v_mov_b32_e32 v189, s11
	v_lshrrev_b32_e32 v190, 8, v189
	v_bfe_u32 v191, v189, 6, 2
	v_lshl_add_u32 v192, v191, 2, v188
	v_lshl_add_u32 v193, v190, 4, v187
	v_mul_u32_u24_e32 v200, 0x110, v193
	v_lshl_add_u32 v200, v191, 5, v200
	v_lshl_add_u32 v200, v188, 3, v200
	v_add_u32_e32 v200, 0x20100, v200
	v_add_u32_e32 v201, 0x2200, v200
	v_lshl_add_u32 v193, v190, 4, v192
	v_mul_u32_u24_e32 v202, 0x110, v193
	v_lshl_add_u32 v202, v187, 4, v202
	v_add_u32_e32 v202, 0x20100, v202
	v_add_u32_e32 v203, 0x2200, v202
	v_sub_u32_e32 v198, v192, v187
	v_mul_i32_i24_e32 v198, 0x1600, v198
	v_lshl_add_u32 v198, v187, 4, v198
	v_lshlrev_b32_e32 v199, 5, v191
	v_sub_u32_e32 v198, v198, v199
	v_lshlrev_b32_e32 v199, 3, v188
	v_sub_u32_e32 v198, v198, v199
	v_ashrrev_i32_e32 v199, 31, v198
	v_mul_f32_e32 v147, 0xbfb8aa3b, v130
	v_exp_f32_e32 v147, v147
	s_or_b32 s9, s18, s39
	s_ashr_i32 s9, s9, 1
	v_add_u32_e32 v146, s16, v5
	v_add_f32_e32 v147, 1.0, v147
	v_rcp_f32_e32 v154, v147
	v_mul_f32_e32 v147, 0xbfb8aa3b, v131
	v_exp_f32_e32 v147, v147
	v_mov_b64_e32 v[144:145], s[28:29]
	s_movk_i32 s11, 0x1600
	v_mad_i64_i32 v[152:153], s[20:21], v146, s11, v[144:145]
	v_add_f32_e32 v147, 1.0, v147
	v_rcp_f32_e32 v155, v147
	s_nop 0
	v_pk_mul_f32 v[130:131], v[130:131], v[154:155]
	s_nop 0
	v_pk_mul_f32 v[126:127], v[126:127], v[130:131]
	s_nop 0
	v_cvt_pk_f16_f32 v130, v126, v127
	v_mul_f32_e32 v126, 0xbfb8aa3b, v132
	v_mul_f32_e32 v127, 0xbfb8aa3b, v133
	v_exp_f32_e32 v126, v126
	v_exp_f32_e32 v127, v127
	v_add_f32_e32 v126, 1.0, v126
	v_add_f32_e32 v127, 1.0, v127
	v_rcp_f32_e32 v126, v126
	v_rcp_f32_e32 v127, v127
	s_nop 0
	v_pk_mul_f32 v[126:127], v[132:133], v[126:127]
	s_nop 0
	v_pk_mul_f32 v[126:127], v[128:129], v[126:127]
	s_nop 0
	v_cvt_pk_f16_f32 v131, v126, v127
	v_or_b32_e32 v126, s9, v150
	v_ashrrev_i32_e32 v127, 31, v126
	v_lshlrev_b64 v[126:127], 1, v[126:127]
	v_lshl_add_u64 v[128:129], v[152:153], 0, v[126:127]
	ds_write_b64 v200, v[130:131]
	v_mul_f32_e32 v130, 0xbfb8aa3b, v122
	v_mul_f32_e32 v131, 0xbfb8aa3b, v123
	v_exp_f32_e32 v130, v130
	v_exp_f32_e32 v131, v131
	v_add_f32_e32 v130, 1.0, v130
	v_add_f32_e32 v131, 1.0, v131
	v_rcp_f32_e32 v130, v130
	v_rcp_f32_e32 v131, v131
	s_nop 0
	v_pk_mul_f32 v[122:123], v[122:123], v[130:131]
	s_nop 0
	v_pk_mul_f32 v[118:119], v[118:119], v[122:123]
	s_nop 0
	v_cvt_pk_f16_f32 v118, v118, v119
	v_mul_f32_e32 v119, 0xbfb8aa3b, v124
	v_exp_f32_e32 v119, v119
	s_nop 0
	v_add_f32_e32 v119, 1.0, v119
	v_rcp_f32_e32 v122, v119
	v_mul_f32_e32 v119, 0xbfb8aa3b, v125
	v_exp_f32_e32 v119, v119
	s_nop 0
	v_add_f32_e32 v119, 1.0, v119
	v_rcp_f32_e32 v123, v119
	s_nop 0
	v_pk_mul_f32 v[122:123], v[124:125], v[122:123]
	s_nop 0
	v_pk_mul_f32 v[120:121], v[120:121], v[122:123]
	s_nop 0
	v_cvt_pk_f16_f32 v119, v120, v121
	ds_write_b64 v200, v[118:119] offset:128
	s_waitcnt lgkmcnt(0)
	s_barrier
	ds_read_b128 v[186:189], v202
	v_lshl_add_u64 v[194:195], v[198:199], 0, v[128:129]
	v_mul_f32_e32 v120, 0xbfb8aa3b, v114
	v_mul_f32_e32 v121, 0xbfb8aa3b, v115
	v_exp_f32_e32 v120, v120
	v_exp_f32_e32 v121, v121
	v_add_u32_e32 v118, 16, v146
	v_mad_i64_i32 v[118:119], s[20:21], v118, s11, v[144:145]
	v_add_f32_e32 v120, 1.0, v120
	v_add_f32_e32 v121, 1.0, v121
	v_rcp_f32_e32 v120, v120
	v_rcp_f32_e32 v121, v121
	s_nop 0
	v_pk_mul_f32 v[114:115], v[114:115], v[120:121]
	s_nop 0
	v_pk_mul_f32 v[110:111], v[110:111], v[114:115]
	s_nop 0
	v_cvt_pk_f16_f32 v110, v110, v111
	v_mul_f32_e32 v111, 0xbfb8aa3b, v116
	v_exp_f32_e32 v111, v111
	s_nop 0
	v_add_f32_e32 v111, 1.0, v111
	v_rcp_f32_e32 v114, v111
	v_mul_f32_e32 v111, 0xbfb8aa3b, v117
	v_exp_f32_e32 v111, v111
	s_nop 0
	v_add_f32_e32 v111, 1.0, v111
	v_rcp_f32_e32 v115, v111
	s_nop 0
	v_pk_mul_f32 v[114:115], v[116:117], v[114:115]
	s_nop 0
	v_pk_mul_f32 v[112:113], v[112:113], v[114:115]
	s_nop 0
	v_cvt_pk_f16_f32 v111, v112, v113
	v_lshl_add_u64 v[112:113], v[118:119], 0, v[126:127]
	s_waitcnt lgkmcnt(0)
	global_store_dwordx4 v[194:195], v[186:189], off
	ds_write_b64 v201, v[110:111]
	v_mul_f32_e32 v110, 0xbfb8aa3b, v106
	v_mul_f32_e32 v111, 0xbfb8aa3b, v107
	v_exp_f32_e32 v110, v110
	v_exp_f32_e32 v111, v111
	v_add_f32_e32 v110, 1.0, v110
	v_add_f32_e32 v111, 1.0, v111
	v_rcp_f32_e32 v110, v110
	v_rcp_f32_e32 v111, v111
	s_nop 0
	v_pk_mul_f32 v[106:107], v[106:107], v[110:111]
	s_nop 0
	v_pk_mul_f32 v[102:103], v[102:103], v[106:107]
	s_nop 0
	v_cvt_pk_f16_f32 v102, v102, v103
	v_mul_f32_e32 v103, 0xbfb8aa3b, v108
	v_exp_f32_e32 v103, v103
	s_nop 0
	v_add_f32_e32 v103, 1.0, v103
	v_rcp_f32_e32 v106, v103
	v_mul_f32_e32 v103, 0xbfb8aa3b, v109
	v_exp_f32_e32 v103, v103
	s_nop 0
	v_add_f32_e32 v103, 1.0, v103
	v_rcp_f32_e32 v107, v103
	s_nop 0
	v_pk_mul_f32 v[106:107], v[108:109], v[106:107]
	s_nop 0
	v_pk_mul_f32 v[104:105], v[104:105], v[106:107]
	s_nop 0
	v_cvt_pk_f16_f32 v103, v104, v105
	ds_write_b64 v201, v[102:103] offset:128
	s_waitcnt lgkmcnt(0)
	s_barrier
; template <int EPI>
; DI void gemm_phase(const int wid_s, const h16* __restrict__ A, const h16* __restrict__ Bt, const int N, const int K, const EpiArgs ea) {
;     ...
;             const int f0 = (bcol + bj * HALF + wc * 32) / 2 + 4 * fq;
;             half4 o;
; #pragma unroll
;             for (int j = 0; j < 4; ++j) { const float g = v0[j], u = v1[j]; o[j] = (h16)(g * __builtin_amdgcn_rcpf(1.f + __builtin_amdgcn_exp2f(g * -1.4426950408889634f)) * u); }
;             *(half4*)(ea.out + row * DFF + f0) = o;
	ds_read_b128 v[190:193], v203
	v_lshl_add_u64 v[196:197], v[198:199], 0, v[112:113]
	v_mul_f32_e32 v104, 0xbfb8aa3b, v98
	v_mul_f32_e32 v105, 0xbfb8aa3b, v99
	v_exp_f32_e32 v104, v104
	v_exp_f32_e32 v105, v105
	v_add_u32_e32 v102, 32, v146
	v_mad_i64_i32 v[102:103], s[20:21], v102, s11, v[144:145]
	v_add_f32_e32 v104, 1.0, v104
	v_add_f32_e32 v105, 1.0, v105
	v_rcp_f32_e32 v104, v104
	v_rcp_f32_e32 v105, v105
	s_nop 0
	v_pk_mul_f32 v[98:99], v[98:99], v[104:105]
	s_nop 0
	v_pk_mul_f32 v[94:95], v[94:95], v[98:99]
	s_nop 0
	v_cvt_pk_f16_f32 v94, v94, v95
	v_mul_f32_e32 v95, 0xbfb8aa3b, v100
	v_exp_f32_e32 v95, v95
	s_nop 0
	v_add_f32_e32 v95, 1.0, v95
	v_rcp_f32_e32 v98, v95
	v_mul_f32_e32 v95, 0xbfb8aa3b, v101
	v_exp_f32_e32 v95, v95
	s_nop 0
	v_add_f32_e32 v95, 1.0, v95
	v_rcp_f32_e32 v99, v95
	s_nop 0
	v_pk_mul_f32 v[98:99], v[100:101], v[98:99]
	s_nop 0
	v_pk_mul_f32 v[96:97], v[96:97], v[98:99]
	s_nop 0
	v_cvt_pk_f16_f32 v95, v96, v97
	v_lshl_add_u64 v[96:97], v[102:103], 0, v[126:127]
	s_waitcnt lgkmcnt(0)
	global_store_dwordx4 v[196:197], v[190:193], off
	ds_write_b64 v200, v[94:95]
	v_mul_f32_e32 v94, 0xbfb8aa3b, v90
	v_mul_f32_e32 v95, 0xbfb8aa3b, v91
	v_exp_f32_e32 v94, v94
	v_exp_f32_e32 v95, v95
	v_add_f32_e32 v94, 1.0, v94
	v_add_f32_e32 v95, 1.0, v95
	v_rcp_f32_e32 v94, v94
	v_rcp_f32_e32 v95, v95
	s_nop 0
	v_pk_mul_f32 v[90:91], v[90:91], v[94:95]
	s_nop 0
	v_pk_mul_f32 v[86:87], v[86:87], v[90:91]
	s_nop 0
	v_cvt_pk_f16_f32 v86, v86, v87
	v_mul_f32_e32 v87, 0xbfb8aa3b, v92
	v_exp_f32_e32 v87, v87
	s_nop 0
	v_add_f32_e32 v87, 1.0, v87
	v_rcp_f32_e32 v90, v87
	v_mul_f32_e32 v87, 0xbfb8aa3b, v93
	v_exp_f32_e32 v87, v87
	s_nop 0
	v_add_f32_e32 v87, 1.0, v87
	v_rcp_f32_e32 v91, v87
	s_nop 0
	v_pk_mul_f32 v[90:91], v[92:93], v[90:91]
	s_nop 0
	v_pk_mul_f32 v[88:89], v[88:89], v[90:91]
	s_nop 0
	v_cvt_pk_f16_f32 v87, v88, v89
	ds_write_b64 v200, v[86:87] offset:128
	s_waitcnt lgkmcnt(0)
	s_barrier
	ds_read_b128 v[186:189], v202
	v_lshl_add_u64 v[194:195], v[198:199], 0, v[96:97]
	v_mul_f32_e32 v88, 0xbfb8aa3b, v82
	v_mul_f32_e32 v89, 0xbfb8aa3b, v83
	v_exp_f32_e32 v88, v88
	v_exp_f32_e32 v89, v89
	v_add_u32_e32 v86, 48, v146
	v_mad_i64_i32 v[86:87], s[20:21], v86, s11, v[144:145]
	v_add_f32_e32 v88, 1.0, v88
	v_add_f32_e32 v89, 1.0, v89
	v_rcp_f32_e32 v88, v88
	v_rcp_f32_e32 v89, v89
	s_nop 0
	v_pk_mul_f32 v[82:83], v[82:83], v[88:89]
	s_nop 0
	v_pk_mul_f32 v[78:79], v[78:79], v[82:83]
	s_nop 0
	v_cvt_pk_f16_f32 v78, v78, v79
	v_mul_f32_e32 v79, 0xbfb8aa3b, v84
	v_exp_f32_e32 v79, v79
	s_nop 0
	v_add_f32_e32 v79, 1.0, v79
	v_rcp_f32_e32 v82, v79
	v_mul_f32_e32 v79, 0xbfb8aa3b, v85
	v_exp_f32_e32 v79, v79
	s_nop 0
	v_add_f32_e32 v79, 1.0, v79
	v_rcp_f32_e32 v83, v79
	s_nop 0
	v_pk_mul_f32 v[82:83], v[84:85], v[82:83]
	s_nop 0
	v_pk_mul_f32 v[80:81], v[80:81], v[82:83]
	s_nop 0
	v_cvt_pk_f16_f32 v79, v80, v81
	v_lshl_add_u64 v[80:81], v[86:87], 0, v[126:127]
	s_waitcnt lgkmcnt(0)
	global_store_dwordx4 v[194:195], v[186:189], off
	ds_write_b64 v201, v[78:79]
	v_mul_f32_e32 v78, 0xbfb8aa3b, v74
	v_mul_f32_e32 v79, 0xbfb8aa3b, v75
	v_exp_f32_e32 v78, v78
	v_exp_f32_e32 v79, v79
	v_add_f32_e32 v78, 1.0, v78
	v_add_f32_e32 v79, 1.0, v79
	v_rcp_f32_e32 v78, v78
	v_rcp_f32_e32 v79, v79
	s_nop 0
	v_pk_mul_f32 v[74:75], v[74:75], v[78:79]
	s_nop 0
	v_pk_mul_f32 v[70:71], v[70:71], v[74:75]
	s_nop 0
	v_cvt_pk_f16_f32 v70, v70, v71
	v_mul_f32_e32 v71, 0xbfb8aa3b, v76
	v_exp_f32_e32 v71, v71
	s_nop 0
	v_add_f32_e32 v71, 1.0, v71
	v_rcp_f32_e32 v74, v71
	v_mul_f32_e32 v71, 0xbfb8aa3b, v77
	v_exp_f32_e32 v71, v71
	s_nop 0
	v_add_f32_e32 v71, 1.0, v71
	v_rcp_f32_e32 v75, v71
	s_nop 0
	v_pk_mul_f32 v[74:75], v[76:77], v[74:75]
	s_nop 0
	v_pk_mul_f32 v[72:73], v[72:73], v[74:75]
	s_nop 0
	v_cvt_pk_f16_f32 v71, v72, v73
	ds_write_b64 v201, v[70:71] offset:128
	s_waitcnt lgkmcnt(0)
	s_barrier
	ds_read_b128 v[190:193], v203
	v_lshl_add_u64 v[196:197], v[198:199], 0, v[80:81]
	v_mul_f32_e32 v72, 0xbfb8aa3b, v66
	v_mul_f32_e32 v73, 0xbfb8aa3b, v67
	v_exp_f32_e32 v72, v72
	v_exp_f32_e32 v73, v73
	v_add_u32_e32 v70, 0x80, v146
	v_mad_i64_i32 v[70:71], s[20:21], v70, s11, v[144:145]
	v_add_f32_e32 v72, 1.0, v72
	v_add_f32_e32 v73, 1.0, v73
	v_rcp_f32_e32 v72, v72
	v_rcp_f32_e32 v73, v73
	s_nop 0
	v_pk_mul_f32 v[66:67], v[66:67], v[72:73]
	s_nop 0
	v_pk_mul_f32 v[62:63], v[62:63], v[66:67]
	s_nop 0
	v_cvt_pk_f16_f32 v62, v62, v63
	v_mul_f32_e32 v63, 0xbfb8aa3b, v68
	v_exp_f32_e32 v63, v63
	s_nop 0
	v_add_f32_e32 v63, 1.0, v63
	v_rcp_f32_e32 v66, v63
	v_mul_f32_e32 v63, 0xbfb8aa3b, v69
	v_exp_f32_e32 v63, v63
	s_nop 0
	v_add_f32_e32 v63, 1.0, v63
	v_rcp_f32_e32 v67, v63
	s_nop 0
	v_pk_mul_f32 v[66:67], v[68:69], v[66:67]
	s_nop 0
	v_pk_mul_f32 v[64:65], v[64:65], v[66:67]
	s_nop 0
	v_cvt_pk_f16_f32 v63, v64, v65
	v_lshl_add_u64 v[64:65], v[70:71], 0, v[126:127]
	s_waitcnt lgkmcnt(0)
	global_store_dwordx4 v[196:197], v[190:193], off
	ds_write_b64 v200, v[62:63]
	v_mul_f32_e32 v62, 0xbfb8aa3b, v58
	v_mul_f32_e32 v63, 0xbfb8aa3b, v59
	v_exp_f32_e32 v62, v62
	v_exp_f32_e32 v63, v63
	v_add_f32_e32 v62, 1.0, v62
	v_add_f32_e32 v63, 1.0, v63
	v_rcp_f32_e32 v62, v62
	v_rcp_f32_e32 v63, v63
	s_nop 0
	v_pk_mul_f32 v[58:59], v[58:59], v[62:63]
	s_nop 0
	v_pk_mul_f32 v[54:55], v[54:55], v[58:59]
	s_nop 0
	v_cvt_pk_f16_f32 v54, v54, v55
	v_mul_f32_e32 v55, 0xbfb8aa3b, v60
	v_exp_f32_e32 v55, v55
	s_nop 0
	v_add_f32_e32 v55, 1.0, v55
	v_rcp_f32_e32 v58, v55
	v_mul_f32_e32 v55, 0xbfb8aa3b, v61
	v_exp_f32_e32 v55, v55
	s_nop 0
	v_add_f32_e32 v55, 1.0, v55
	v_rcp_f32_e32 v59, v55
	s_nop 0
	v_pk_mul_f32 v[58:59], v[60:61], v[58:59]
	s_nop 0
	v_pk_mul_f32 v[56:57], v[56:57], v[58:59]
	s_nop 0
	v_cvt_pk_f16_f32 v55, v56, v57
	ds_write_b64 v200, v[54:55] offset:128
	s_waitcnt lgkmcnt(0)
	s_barrier
; #define BAR __builtin_amdgcn_s_barrier()
; template <int EPI>
; DI void gemm_phase(const int wid_s, const h16* __restrict__ A, const h16* __restrict__ Bt, const int N, const int K, const EpiArgs ea) {
;     ...
;             const int f0 = (bcol + bj * HALF + wc * 32) / 2 + 4 * fq;
;             half4 o;
; #pragma unroll
;             for (int j = 0; j < 4; ++j) { const float g = v0[j], u = v1[j]; o[j] = (h16)(g * __builtin_amdgcn_rcpf(1.f + __builtin_amdgcn_exp2f(g * -1.4426950408889634f)) * u); }
;             *(half4*)(ea.out + row * DFF + f0) = o;
;     ...
;     if (!has_next) break;
; #pragma unroll
;     for (int a = 0; a < 2; ++a)
; #pragma unroll
;       for (int b = 0; b < 2; ++b)
; #pragma unroll
;         for (int m = 0; m < 4; ++m)
; #pragma unroll
;           for (int n = 0; n < 2; ++n) acc[a][b][m][n] = (f32x4){0.f, 0.f, 0.f, 0.f};
;     L = Ln; brow = nbrow; bcol = nbcol; cA = nA; cB = nB;
;     if (wr == 1) BAR;
	ds_read_b128 v[186:189], v202
	v_lshl_add_u64 v[194:195], v[198:199], 0, v[64:65]
	v_mul_f32_e32 v56, 0xbfb8aa3b, v50
	v_mul_f32_e32 v57, 0xbfb8aa3b, v51
	v_exp_f32_e32 v56, v56
	v_exp_f32_e32 v57, v57
	v_add_u32_e32 v54, 0x90, v146
	v_mad_i64_i32 v[54:55], s[20:21], v54, s11, v[144:145]
	v_add_f32_e32 v56, 1.0, v56
	v_add_f32_e32 v57, 1.0, v57
	v_rcp_f32_e32 v56, v56
	v_rcp_f32_e32 v57, v57
	s_nop 0
	v_pk_mul_f32 v[50:51], v[50:51], v[56:57]
	s_nop 0
	v_pk_mul_f32 v[46:47], v[46:47], v[50:51]
	s_nop 0
	v_cvt_pk_f16_f32 v46, v46, v47
	v_mul_f32_e32 v47, 0xbfb8aa3b, v52
	v_exp_f32_e32 v47, v47
	s_nop 0
	v_add_f32_e32 v47, 1.0, v47
	v_rcp_f32_e32 v50, v47
	v_mul_f32_e32 v47, 0xbfb8aa3b, v53
	v_exp_f32_e32 v47, v47
	s_nop 0
	v_add_f32_e32 v47, 1.0, v47
	v_rcp_f32_e32 v51, v47
	s_nop 0
	v_pk_mul_f32 v[50:51], v[52:53], v[50:51]
	s_nop 0
	v_pk_mul_f32 v[48:49], v[48:49], v[50:51]
	s_nop 0
	v_cvt_pk_f16_f32 v47, v48, v49
	v_lshl_add_u64 v[48:49], v[54:55], 0, v[126:127]
	s_waitcnt lgkmcnt(0)
	global_store_dwordx4 v[194:195], v[186:189], off
	ds_write_b64 v201, v[46:47]
	v_mul_f32_e32 v46, 0xbfb8aa3b, v42
	v_mul_f32_e32 v47, 0xbfb8aa3b, v43
	v_exp_f32_e32 v46, v46
	v_exp_f32_e32 v47, v47
	v_add_f32_e32 v46, 1.0, v46
	v_add_f32_e32 v47, 1.0, v47
	v_rcp_f32_e32 v46, v46
	v_rcp_f32_e32 v47, v47
	s_nop 0
	v_pk_mul_f32 v[42:43], v[42:43], v[46:47]
	s_nop 0
	v_pk_mul_f32 v[38:39], v[38:39], v[42:43]
	s_nop 0
	v_cvt_pk_f16_f32 v38, v38, v39
	v_mul_f32_e32 v39, 0xbfb8aa3b, v44
	v_exp_f32_e32 v39, v39
	s_nop 0
	v_add_f32_e32 v39, 1.0, v39
	v_rcp_f32_e32 v42, v39
	v_mul_f32_e32 v39, 0xbfb8aa3b, v45
	v_exp_f32_e32 v39, v39
	s_nop 0
	v_add_f32_e32 v39, 1.0, v39
	v_rcp_f32_e32 v43, v39
	s_nop 0
	v_pk_mul_f32 v[42:43], v[44:45], v[42:43]
	s_nop 0
	v_pk_mul_f32 v[40:41], v[40:41], v[42:43]
	s_nop 0
	v_cvt_pk_f16_f32 v39, v40, v41
	ds_write_b64 v201, v[38:39] offset:128
	s_waitcnt lgkmcnt(0)
	s_barrier
	ds_read_b128 v[190:193], v203
	v_lshl_add_u64 v[196:197], v[198:199], 0, v[48:49]
	v_mul_f32_e32 v40, 0xbfb8aa3b, v34
	v_mul_f32_e32 v41, 0xbfb8aa3b, v35
	v_exp_f32_e32 v40, v40
	v_exp_f32_e32 v41, v41
	v_add_u32_e32 v38, 0xa0, v146
	v_mad_i64_i32 v[38:39], s[20:21], v38, s11, v[144:145]
	v_add_f32_e32 v40, 1.0, v40
	v_add_f32_e32 v41, 1.0, v41
	v_rcp_f32_e32 v40, v40
	v_rcp_f32_e32 v41, v41
	s_nop 0
	v_pk_mul_f32 v[34:35], v[34:35], v[40:41]
	s_nop 0
	v_pk_mul_f32 v[30:31], v[30:31], v[34:35]
	s_nop 0
	v_cvt_pk_f16_f32 v30, v30, v31
	v_mul_f32_e32 v31, 0xbfb8aa3b, v36
	v_exp_f32_e32 v31, v31
	s_nop 0
	v_add_f32_e32 v31, 1.0, v31
	v_rcp_f32_e32 v34, v31
	v_mul_f32_e32 v31, 0xbfb8aa3b, v37
	v_exp_f32_e32 v31, v31
	s_nop 0
	v_add_f32_e32 v31, 1.0, v31
	v_rcp_f32_e32 v35, v31
	s_nop 0
	v_pk_mul_f32 v[34:35], v[36:37], v[34:35]
	s_nop 0
	v_pk_mul_f32 v[32:33], v[32:33], v[34:35]
	s_nop 0
	v_cvt_pk_f16_f32 v31, v32, v33
	v_lshl_add_u64 v[32:33], v[38:39], 0, v[126:127]
	s_waitcnt lgkmcnt(0)
	global_store_dwordx4 v[196:197], v[190:193], off
	ds_write_b64 v200, v[30:31]
	v_mul_f32_e32 v30, 0xbfb8aa3b, v26
	v_mul_f32_e32 v31, 0xbfb8aa3b, v27
	v_exp_f32_e32 v30, v30
	v_exp_f32_e32 v31, v31
	v_add_f32_e32 v30, 1.0, v30
	v_add_f32_e32 v31, 1.0, v31
	v_rcp_f32_e32 v30, v30
	v_rcp_f32_e32 v31, v31
	s_nop 0
	v_pk_mul_f32 v[26:27], v[26:27], v[30:31]
	s_nop 0
	v_pk_mul_f32 v[22:23], v[22:23], v[26:27]
	s_nop 0
	v_cvt_pk_f16_f32 v22, v22, v23
	v_mul_f32_e32 v23, 0xbfb8aa3b, v28
	v_exp_f32_e32 v23, v23
	s_nop 0
	v_add_f32_e32 v23, 1.0, v23
	v_rcp_f32_e32 v26, v23
	v_mul_f32_e32 v23, 0xbfb8aa3b, v29
	v_exp_f32_e32 v23, v23
	s_nop 0
	v_add_f32_e32 v23, 1.0, v23
	v_rcp_f32_e32 v27, v23
	s_nop 0
	v_pk_mul_f32 v[26:27], v[28:29], v[26:27]
	s_nop 0
	v_pk_mul_f32 v[24:25], v[24:25], v[26:27]
	s_nop 0
	v_cvt_pk_f16_f32 v23, v24, v25
	ds_write_b64 v200, v[22:23] offset:128
	s_waitcnt lgkmcnt(0)
	s_barrier
	ds_read_b128 v[186:189], v202
	v_lshl_add_u64 v[194:195], v[198:199], 0, v[32:33]
	v_mul_f32_e32 v24, 0xbfb8aa3b, v18
	v_mul_f32_e32 v25, 0xbfb8aa3b, v19
	v_exp_f32_e32 v24, v24
	v_exp_f32_e32 v25, v25
	v_add_u32_e32 v22, 0xb0, v146
	v_mad_i64_i32 v[22:23], s[20:21], v22, s11, v[144:145]
	v_add_f32_e32 v24, 1.0, v24
	v_add_f32_e32 v25, 1.0, v25
	v_rcp_f32_e32 v24, v24
	v_rcp_f32_e32 v25, v25
	s_nop 0
	v_pk_mul_f32 v[18:19], v[18:19], v[24:25]
	s_nop 0
	v_pk_mul_f32 v[14:15], v[14:15], v[18:19]
	s_nop 0
	v_cvt_pk_f16_f32 v14, v14, v15
	v_mul_f32_e32 v15, 0xbfb8aa3b, v20
	v_exp_f32_e32 v15, v15
	s_nop 0
	v_add_f32_e32 v15, 1.0, v15
	v_rcp_f32_e32 v18, v15
	v_mul_f32_e32 v15, 0xbfb8aa3b, v21
	v_exp_f32_e32 v15, v15
	s_nop 0
	v_add_f32_e32 v15, 1.0, v15
	v_rcp_f32_e32 v19, v15
	s_nop 0
	v_pk_mul_f32 v[18:19], v[20:21], v[18:19]
	s_nop 0
	v_pk_mul_f32 v[16:17], v[16:17], v[18:19]
	s_nop 0
	v_cvt_pk_f16_f32 v15, v16, v17
	v_lshl_add_u64 v[16:17], v[22:23], 0, v[126:127]
	s_waitcnt lgkmcnt(0)
	global_store_dwordx4 v[194:195], v[186:189], off
	ds_write_b64 v201, v[14:15]
	v_mul_f32_e32 v14, 0xbfb8aa3b, v10
	v_mul_f32_e32 v15, 0xbfb8aa3b, v11
	v_exp_f32_e32 v14, v14
	v_exp_f32_e32 v15, v15
	v_add_f32_e32 v14, 1.0, v14
	v_add_f32_e32 v15, 1.0, v15
	v_rcp_f32_e32 v14, v14
	v_rcp_f32_e32 v15, v15
	s_nop 0
	v_pk_mul_f32 v[10:11], v[10:11], v[14:15]
	s_nop 0
	v_pk_mul_f32 v[6:7], v[6:7], v[10:11]
	s_nop 0
	v_cvt_pk_f16_f32 v6, v6, v7
	v_mul_f32_e32 v7, 0xbfb8aa3b, v12
	v_exp_f32_e32 v7, v7
	s_nop 0
	v_add_f32_e32 v7, 1.0, v7
	v_rcp_f32_e32 v10, v7
	v_mul_f32_e32 v7, 0xbfb8aa3b, v13
	v_exp_f32_e32 v7, v7
	s_nop 0
	v_add_f32_e32 v7, 1.0, v7
	v_rcp_f32_e32 v11, v7
	s_nop 0
	v_pk_mul_f32 v[10:11], v[12:13], v[10:11]
	s_nop 0
	v_pk_mul_f32 v[8:9], v[8:9], v[10:11]
	s_nop 0
	v_cvt_pk_f16_f32 v7, v8, v9
	ds_write_b64 v201, v[6:7] offset:128
	s_waitcnt lgkmcnt(0)
	s_barrier
	ds_read_b128 v[190:193], v203
	v_lshl_add_u64 v[196:197], v[198:199], 0, v[16:17]
	s_waitcnt lgkmcnt(0)
	global_store_dwordx4 v[196:197], v[190:193], off
	v_readlane_b32 s48, v249, 37
	v_readlane_b32 s50, v249, 41
	s_andn2_b64 vcc, exec, s[6:7]
	s_mov_b64 s[6:7], -1
	s_movk_i32 s26, 0x1fff
	v_readlane_b32 s49, v249, 38
	v_readlane_b32 s51, v249, 42
	s_cbranch_vccnz .LBB0_137
	s_andn2_b64 vcc, exec, s[0:1]
	s_cbranch_vccnz .LBB0_136
	s_barrier
	s_branch .LBB0_136
